# P6 output rows written with non-temporal stores
# baseline (speedup 1.0000x reference)
.LBB0_1058:
	v_or_b32_e32 v1, s34, v147
	v_and_b32_e32 v0, 64, v146
	v_lshlrev_b32_e32 v2, 2, v148
	v_add3_u32 v68, v1, v154, s15
	v_or3_b32 v2, v2, v0, s42
	v_ashrrev_i32_e32 v0, 12, v68
	v_mul_i32_i24_e32 v0, 0xc00, v0
	v_readlane_b32 s48, v234, 16
	v_ashrrev_i32_e32 v1, 31, v0
	v_readlane_b32 s49, v234, 17
	v_ashrrev_i32_e32 v69, 31, v68
	v_readlane_b32 s0, v234, 14
	v_lshl_add_u64 v[0:1], v[0:1], 2, s[48:49]
	v_lshl_add_u64 v[78:79], v[0:1], 0, s[80:81]
	v_lshlrev_b64 v[0:1], 12, v[68:69]
	v_readlane_b32 s1, v234, 15
	v_lshlrev_b32_e32 v2, 2, v2
	v_lshl_add_u64 v[74:75], v[78:79], 0, v[2:3]
	v_lshl_add_u64 v[70:71], s[0:1], 0, v[0:1]
	v_lshl_add_u64 v[80:81], v[70:71], 0, v[2:3]
	global_load_dwordx4 v[70:73], v[80:81], off
	v_readlane_b32 s40, v237, 0
	global_load_dwordx4 v[74:77], v[74:75], off
	v_readlane_b32 s41, v237, 1
	v_readlane_b32 s42, v237, 2
	v_readlane_b32 s43, v237, 3
	v_readlane_b32 s44, v237, 4
	v_readlane_b32 s45, v237, 5
	v_readlane_b32 s46, v237, 6
	v_readlane_b32 s47, v237, 7
	s_mov_b64 s[40:41], s[44:45]
	s_mov_b64 s[42:43], s[46:47]
	v_lshl_add_u64 v[0:1], s[42:43], 0, v[0:1]
	s_add_i32 s13, s13, s33
	s_waitcnt vmcnt(0)
	v_pk_fma_f32 v[66:67], v[66:67], v[76:77], v[72:73]
	v_pk_fma_f32 v[64:65], v[64:65], v[74:75], v[70:71]
	v_lshl_add_u64 v[74:75], v[0:1], 0, v[2:3]
	v_or_b32_e32 v0, 64, v2
	v_mov_b32_e32 v1, v3
	global_store_dwordx4 v[74:75], v[64:67], off nt
	v_lshl_add_u64 v[70:71], v[78:79], 0, v[0:1]
	global_load_dwordx4 v[64:67], v[80:81], off offset:64
	s_nop 0
	global_load_dwordx4 v[70:73], v[70:71], off
	s_waitcnt vmcnt(0)
	v_pk_fma_f32 v[62:63], v[62:63], v[72:73], v[66:67]
	v_pk_fma_f32 v[60:61], v[60:61], v[70:71], v[64:65]
	global_store_dwordx4 v[74:75], v[60:63], off offset:64 nt
	global_load_dwordx4 v[62:65], v[80:81], off offset:128
	s_nop 0
	v_or_b32_e32 v60, 0x80, v2
	v_mov_b32_e32 v61, v3
	v_lshl_add_u64 v[66:67], v[78:79], 0, v[60:61]
	global_load_dwordx4 v[70:73], v[66:67], off
	s_waitcnt vmcnt(0)
	v_pk_fma_f32 v[58:59], v[58:59], v[72:73], v[64:65]
	v_pk_fma_f32 v[56:57], v[56:57], v[70:71], v[62:63]
	global_store_dwordx4 v[74:75], v[56:59], off offset:128 nt
	global_load_dwordx4 v[62:65], v[80:81], off offset:192
	s_nop 0
	v_or_b32_e32 v56, 0xc0, v2
	v_mov_b32_e32 v57, v3
	v_lshl_add_u64 v[58:59], v[78:79], 0, v[56:57]
	global_load_dwordx4 v[70:73], v[58:59], off
	s_waitcnt vmcnt(0)
	v_pk_fma_f32 v[54:55], v[54:55], v[72:73], v[64:65]
	v_pk_fma_f32 v[52:53], v[52:53], v[70:71], v[62:63]
	global_store_dwordx4 v[74:75], v[52:55], off offset:192 nt
	s_nop 1
	v_add_u32_e32 v52, 16, v68
	v_ashrrev_i32_e32 v53, 12, v52
	v_mul_i32_i24_e32 v54, 0xc00, v53
	v_ashrrev_i32_e32 v55, 31, v54
	v_ashrrev_i32_e32 v53, 31, v52
	v_lshl_add_u64 v[54:55], v[54:55], 2, s[48:49]
	v_lshlrev_b64 v[66:67], 12, v[52:53]
	v_lshl_add_u64 v[58:59], v[54:55], 0, s[80:81]
	v_lshl_add_u64 v[52:53], s[0:1], 0, v[66:67]
	v_lshl_add_u64 v[70:71], v[52:53], 0, v[2:3]
	v_lshl_add_u64 v[62:63], v[58:59], 0, v[2:3]
	global_load_dwordx4 v[52:55], v[70:71], off
	s_nop 0
	global_load_dwordx4 v[62:65], v[62:63], off
	s_waitcnt vmcnt(0)
	v_pk_fma_f32 v[48:49], v[48:49], v[62:63], v[52:53]
	v_lshl_add_u64 v[52:53], s[42:43], 0, v[66:67]
	v_pk_fma_f32 v[50:51], v[50:51], v[64:65], v[54:55]
	v_lshl_add_u64 v[62:63], v[52:53], 0, v[2:3]
	global_store_dwordx4 v[62:63], v[48:51], off nt
	v_lshl_add_u64 v[52:53], v[58:59], 0, v[0:1]
	global_load_dwordx4 v[48:51], v[70:71], off offset:64
	s_nop 0
	global_load_dwordx4 v[52:55], v[52:53], off
	s_waitcnt vmcnt(0)
	v_pk_fma_f32 v[46:47], v[46:47], v[54:55], v[50:51]
	v_pk_fma_f32 v[44:45], v[44:45], v[52:53], v[48:49]
	global_store_dwordx4 v[62:63], v[44:47], off offset:64 nt
	v_lshl_add_u64 v[48:49], v[58:59], 0, v[60:61]
	global_load_dwordx4 v[44:47], v[70:71], off offset:128
	s_nop 0
	global_load_dwordx4 v[48:51], v[48:49], off
	s_waitcnt vmcnt(0)
	v_pk_fma_f32 v[42:43], v[42:43], v[50:51], v[46:47]
	v_pk_fma_f32 v[40:41], v[40:41], v[48:49], v[44:45]
	global_store_dwordx4 v[62:63], v[40:43], off offset:128 nt
	v_lshl_add_u64 v[44:45], v[58:59], 0, v[56:57]
	global_load_dwordx4 v[40:43], v[70:71], off offset:192
	s_nop 0
	global_load_dwordx4 v[44:47], v[44:45], off
	s_waitcnt vmcnt(0)
	v_pk_fma_f32 v[38:39], v[38:39], v[46:47], v[42:43]
	v_pk_fma_f32 v[36:37], v[36:37], v[44:45], v[40:41]
	global_store_dwordx4 v[62:63], v[36:39], off offset:192 nt
	s_nop 1
	v_add_u32_e32 v36, 32, v68
	v_ashrrev_i32_e32 v37, 12, v36
	v_mul_i32_i24_e32 v38, 0xc00, v37
	v_ashrrev_i32_e32 v39, 31, v38
	v_ashrrev_i32_e32 v37, 31, v36
	v_lshl_add_u64 v[38:39], v[38:39], 2, s[48:49]
	v_lshlrev_b64 v[46:47], 12, v[36:37]
	v_lshl_add_u64 v[44:45], v[38:39], 0, s[80:81]
	v_lshl_add_u64 v[36:37], s[0:1], 0, v[46:47]
	v_lshl_add_u64 v[48:49], v[36:37], 0, v[2:3]
	v_lshl_add_u64 v[40:41], v[44:45], 0, v[2:3]
	global_load_dwordx4 v[36:39], v[48:49], off
	s_nop 0
	global_load_dwordx4 v[40:43], v[40:41], off
	s_waitcnt vmcnt(0)
	v_pk_fma_f32 v[32:33], v[32:33], v[40:41], v[36:37]
	v_lshl_add_u64 v[36:37], s[42:43], 0, v[46:47]
	v_pk_fma_f32 v[34:35], v[34:35], v[42:43], v[38:39]
	v_lshl_add_u64 v[40:41], v[36:37], 0, v[2:3]
	global_store_dwordx4 v[40:41], v[32:35], off nt
	v_lshl_add_u64 v[36:37], v[44:45], 0, v[0:1]
	global_load_dwordx4 v[32:35], v[48:49], off offset:64
	s_nop 0
	global_load_dwordx4 v[36:39], v[36:37], off
	s_waitcnt vmcnt(0)
	v_pk_fma_f32 v[30:31], v[30:31], v[38:39], v[34:35]
	v_pk_fma_f32 v[28:29], v[28:29], v[36:37], v[32:33]
	global_store_dwordx4 v[40:41], v[28:31], off offset:64 nt
	v_lshl_add_u64 v[32:33], v[44:45], 0, v[60:61]
	global_load_dwordx4 v[28:31], v[48:49], off offset:128
	s_nop 0
	global_load_dwordx4 v[32:35], v[32:33], off
	s_waitcnt vmcnt(0)
	v_pk_fma_f32 v[26:27], v[26:27], v[34:35], v[30:31]
	v_pk_fma_f32 v[24:25], v[24:25], v[32:33], v[28:29]
	global_store_dwordx4 v[40:41], v[24:27], off offset:128 nt
	v_lshl_add_u64 v[28:29], v[44:45], 0, v[56:57]
	global_load_dwordx4 v[24:27], v[48:49], off offset:192
	s_nop 0
	global_load_dwordx4 v[28:31], v[28:29], off
	s_waitcnt vmcnt(0)
	v_pk_fma_f32 v[22:23], v[22:23], v[30:31], v[26:27]
	v_pk_fma_f32 v[20:21], v[20:21], v[28:29], v[24:25]
	global_store_dwordx4 v[40:41], v[20:23], off offset:192 nt
	s_nop 1
	v_add_u32_e32 v20, 48, v68
	v_ashrrev_i32_e32 v21, 12, v20
	v_mul_i32_i24_e32 v22, 0xc00, v21
	v_ashrrev_i32_e32 v23, 31, v22
	v_ashrrev_i32_e32 v21, 31, v20
	v_lshl_add_u64 v[22:23], v[22:23], 2, s[48:49]
	v_lshlrev_b64 v[30:31], 12, v[20:21]
	v_lshl_add_u64 v[28:29], v[22:23], 0, s[80:81]
	v_lshl_add_u64 v[20:21], s[0:1], 0, v[30:31]
	v_lshl_add_u64 v[32:33], v[20:21], 0, v[2:3]
	v_lshl_add_u64 v[24:25], v[28:29], 0, v[2:3]
	global_load_dwordx4 v[20:23], v[32:33], off
	v_lshl_add_u64 v[0:1], v[28:29], 0, v[0:1]
	global_load_dwordx4 v[24:27], v[24:25], off
	v_readlane_b32 s0, v235, 30
	s_add_i32 s12, s12, s0
	s_cmpk_gt_u32 s13, 0x7f
	s_waitcnt vmcnt(0)
	v_pk_fma_f32 v[16:17], v[16:17], v[24:25], v[20:21]
	v_lshl_add_u64 v[20:21], s[42:43], 0, v[30:31]
	v_pk_fma_f32 v[18:19], v[18:19], v[26:27], v[22:23]
	v_lshl_add_u64 v[24:25], v[20:21], 0, v[2:3]
	global_store_dwordx4 v[24:25], v[16:19], off nt
	global_load_dwordx4 v[16:19], v[32:33], off offset:64
	s_nop 0
	global_load_dwordx4 v[20:23], v[0:1], off
	v_lshl_add_u64 v[0:1], v[28:29], 0, v[60:61]
	s_waitcnt vmcnt(0)
	v_pk_fma_f32 v[14:15], v[14:15], v[22:23], v[18:19]
	v_pk_fma_f32 v[12:13], v[12:13], v[20:21], v[16:17]
	global_store_dwordx4 v[24:25], v[12:15], off offset:64 nt
	global_load_dwordx4 v[12:15], v[32:33], off offset:128
	s_nop 0
	global_load_dwordx4 v[16:19], v[0:1], off
	v_lshl_add_u64 v[0:1], v[28:29], 0, v[56:57]
	s_waitcnt vmcnt(0)
	v_pk_fma_f32 v[10:11], v[10:11], v[18:19], v[14:15]
	v_pk_fma_f32 v[8:9], v[8:9], v[16:17], v[12:13]
	global_store_dwordx4 v[24:25], v[8:11], off offset:128 nt
	global_load_dwordx4 v[8:11], v[32:33], off offset:192
	s_nop 0
	global_load_dwordx4 v[12:15], v[0:1], off
	s_waitcnt vmcnt(0)
	v_pk_fma_f32 v[6:7], v[6:7], v[14:15], v[10:11]
	v_pk_fma_f32 v[4:5], v[4:5], v[12:13], v[8:9]
	global_store_dwordx4 v[24:25], v[4:7], off offset:192 nt
	s_cbranch_scc1 .LBB0_255
